# attention unit entry: output accumulators zeroed with 32 v_mov_b64 instead of 64 v_mov_b32
# speedup vs baseline: 1.0058x; 1.0058x over previous
; __device__ __forceinline__ void bias_init(f32x16& p0, f32x16& p1, float base, float nslope2, float nM2, int rel  ) {
;     if (rel <= -63 || rel >= 31) {
;         const float sg = (rel < 0) ? -nslope2 : nslope2, lbv = fmaf(-sg, base, nM2);
; #pragma unroll
;         for (int r = 0; r < 16; ++r) { p0[r] = fmaf((float)((r & 3) + 8 * (r >> 2)), sg, lbv); p1[r] = fmaf((float)((r & 3) + 8 * (r >> 2) + 32), sg, lbv); }
;     } else {
; #pragma unroll
;         for (int r = 0; r < 16; ++r) { const float d = base - (float)((r & 3) + 8 * (r >> 2));
;             p0[r] = fmaf(fabsf(d), nslope2, nM2); p1[r] = fmaf(fabsf(d - 32.f), nslope2, nM2); }
;     }
; }
; __device__ __forceinline__ void diff_unit(const DiffArgs& A, int b, int h, int qb, char* lds, int wv) {
;     ...
;     float l_reg = 0; f32x16 o[4] = {}; bf16x8 qr[4];
;     { const char* Qw = Pb + (size_t)(qb * 128 + wq * 32) * (INC * 2) + (C_DQ + c * 64) * 2; const unsigned qoff = (unsigned)((r32 * INC + hi * 8) * 2);
; #pragma unroll
;       for (int d0 = 0; d0 < 4; ++d0) qr[d0] = *reinterpret_cast<const bf16x8*>(Qw + qoff + d0 * 32); }
;     const int colB0 = c * 128;
;     const int krow = wid * 4 + (lane >> 4), kcc = (lane & 15) ^ (krow & 15);
;     const unsigned koff = (unsigned)((krow * INC + kcc * 8) * 2);
;     const int vkey = (wid >> 2) * 16 + (((wid >> 1) & 1) << 3) + (((lane >> 4) & 1) << 2) + ((lane >> 2) & 3)  , vcol = ((wid & 1) * 2 + (lane >> 5)) * 32 + (lane & 3) * 8;
;     const unsigned voff = (unsigned)((vkey * INC + vcol) * 2 + (C_DV - C_DK) * 2);
;     const int vb0 = (int)(uintptr_t)V_lds + v_rd_base(lane);
;     const char* Pk = Pb + (size_t)(t_lo * KVBLK) * (INC * 2) + C_DK * 2; int iposk = ipos - t_lo * KVBLK - 4 * hi; asm volatile("" : "+v"(iposk));     const int relw = t_lo * KVBLK - (qb * 128 + wq * 32);
;     typedef __attribute__((address_space(3))) unsigned lds_u32;
;     __attribute__((address_space(3))) unsigned char* ldsA = (__attribute__((address_space(3))) unsigned char*)lds + wid * 1024;
;     ...
;     f32x16 pA0, pA1, pB0, pB1; bf16x8 pa0, pa1, pa2, pa3; const int NT = nt;
;     STAGE(0); ENDI();
;     STAGE(1);
;     BIAS(pA0, pA1, 0); qkt<4>(pA0, pA1, K_lds, qr, r32, hi, colB0);
;     ...
;     if (c == 0) {
;     ...
;         const int lp_ = opaque_tid(wv) & 63, r32p = lp_ & 31, hip = lp_ >> 5;
;         exp_half(pA0);
.Lsym_entry:
	v_mov_b64_e32 v[0:1], 0
	v_mov_b64_e32 v[2:3], 0
	v_mov_b64_e32 v[4:5], 0
	v_mov_b64_e32 v[6:7], 0
	v_mov_b64_e32 v[8:9], 0
	v_mov_b64_e32 v[10:11], 0
	v_mov_b64_e32 v[12:13], 0
	v_mov_b64_e32 v[14:15], 0
	v_mov_b64_e32 v[16:17], 0
	v_mov_b64_e32 v[18:19], 0
	v_mov_b64_e32 v[20:21], 0
	v_mov_b64_e32 v[22:23], 0
	v_mov_b64_e32 v[24:25], 0
	v_mov_b64_e32 v[26:27], 0
	v_mov_b64_e32 v[28:29], 0
	v_mov_b64_e32 v[30:31], 0
	v_mov_b64_e32 v[32:33], 0
	v_mov_b64_e32 v[34:35], 0
	v_mov_b64_e32 v[36:37], 0
	v_mov_b64_e32 v[38:39], 0
	v_mov_b64_e32 v[40:41], 0
	v_mov_b64_e32 v[42:43], 0
	v_mov_b64_e32 v[44:45], 0
	v_mov_b64_e32 v[46:47], 0
	v_mov_b64_e32 v[48:49], 0
	v_mov_b64_e32 v[50:51], 0
	v_mov_b64_e32 v[52:53], 0
	v_mov_b64_e32 v[54:55], 0
	v_mov_b64_e32 v[56:57], 0
	v_mov_b64_e32 v[58:59], 0
	v_mov_b64_e32 v[60:61], 0
	v_mov_b64_e32 v[62:63], 0
	v_mov_b32_e32 v182, 0
	v_mbcnt_lo_u32_b32 v190, -1, 0
	v_mbcnt_hi_u32_b32 v190, -1, v190
	v_and_b32_e32 v191, 31, v190
	v_lshrrev_b32_e32 v187, 5, v190
	v_lshlrev_b32_e32 v185, 4, v187
	v_or_b32_e32 v185, s52, v185
	v_and_b32_e32 v183, 15, v191
	v_lshlrev_b32_e32 v183, 4, v183
	v_xor_b32_e32 v185, v185, v183
	v_lshlrev_b32_e32 v183, 8, v191
	v_xor_b32_e32 v178, 0, v185
	v_add_u32_e32 v178, v178, v183
	v_add_u32_e32 v178, 0x10000, v178
	v_xor_b32_e32 v179, 32, v185
	v_add_u32_e32 v179, v179, v183
	v_add_u32_e32 v179, 0x10000, v179
	v_xor_b32_e32 v180, 64, v185
	v_add_u32_e32 v180, v180, v183
	v_add_u32_e32 v180, 0x10000, v180
	v_xor_b32_e32 v181, 96, v185
	v_add_u32_e32 v181, v181, v183
	v_add_u32_e32 v181, 0x10000, v181
	s_add_i32 s55, s63, 64
	v_subrev_u32_e32 v183, 64, v236
	v_cvt_f32_i32_e32 v183, v183
	s_mov_b32 s54, 0
	s_add_u32 s56, s20, 0x1c1e00
	s_addc_u32 s57, s21, 0
	v_exp_f32_e32 v80, v80
	v_exp_f32_e32 v81, v81
	v_exp_f32_e32 v82, v82
	v_exp_f32_e32 v83, v83
	v_add_f32_e32 v182, v80, v182
	v_add_f32_e32 v182, v81, v182
	v_cvt_pk_bf16_f32 v128, v80, v81
	v_exp_f32_e32 v84, v84
	v_exp_f32_e32 v85, v85
	v_add_f32_e32 v182, v82, v182
	v_add_f32_e32 v182, v83, v182
	v_cvt_pk_bf16_f32 v129, v82, v83
	v_exp_f32_e32 v86, v86
	v_exp_f32_e32 v87, v87
	v_add_f32_e32 v182, v84, v182
	v_add_f32_e32 v182, v85, v182
	v_cvt_pk_bf16_f32 v130, v84, v85
	v_cvt_pk_bf16_f32 v131, v86, v87
	v_add_f32_e32 v182, v86, v182
	v_add_f32_e32 v182, v87, v182
	s_add_i32 s100, s55, 62
	s_cmp_lt_u32 s100, 93
	s_cbranch_scc1 .Lsym_diag_n
	s_cmp_lt_i32 s55, 0
	s_cselect_b32 s100, -1.0, 1.0
	v_mul_f32_e32 v185, s100, v186
	v_fma_f32 v187, -v185, v183, s16
	v_fmamk_f32 v112, v185, 0x00000000, v187
	v_fmamk_f32 v96, v185, 0x42000000, v187
	v_fmamk_f32 v113, v185, 0x3f800000, v187
	v_fmamk_f32 v97, v185, 0x42040000, v187
	v_fmamk_f32 v114, v185, 0x40000000, v187
	v_fmamk_f32 v98, v185, 0x42080000, v187
	v_fmamk_f32 v115, v185, 0x40400000, v187
	v_fmamk_f32 v99, v185, 0x420c0000, v187
	v_fmamk_f32 v116, v185, 0x41000000, v187
	v_fmamk_f32 v100, v185, 0x42200000, v187
	v_fmamk_f32 v117, v185, 0x41100000, v187
	v_fmamk_f32 v101, v185, 0x42240000, v187
	v_fmamk_f32 v118, v185, 0x41200000, v187
	v_fmamk_f32 v102, v185, 0x42280000, v187
	v_fmamk_f32 v119, v185, 0x41300000, v187
	v_fmamk_f32 v103, v185, 0x422c0000, v187
	v_fmamk_f32 v120, v185, 0x41800000, v187
	v_fmamk_f32 v104, v185, 0x42400000, v187
	v_fmamk_f32 v121, v185, 0x41880000, v187
	v_fmamk_f32 v105, v185, 0x42440000, v187
	v_fmamk_f32 v122, v185, 0x41900000, v187
	v_fmamk_f32 v106, v185, 0x42480000, v187
	v_fmamk_f32 v123, v185, 0x41980000, v187
	v_fmamk_f32 v107, v185, 0x424c0000, v187
	v_fmamk_f32 v124, v185, 0x41c00000, v187
	v_fmamk_f32 v108, v185, 0x42600000, v187
	v_fmamk_f32 v125, v185, 0x41c80000, v187
	v_fmamk_f32 v109, v185, 0x42640000, v187
	v_fmamk_f32 v126, v185, 0x41d00000, v187
	v_fmamk_f32 v110, v185, 0x42680000, v187
	v_fmamk_f32 v127, v185, 0x41d80000, v187
	v_fmamk_f32 v111, v185, 0x426c0000, v187
	s_branch .Lsym_biasdone_n
